# v092 + nt on the residual-stream (Hb) stores of the row phases P5/P8/P12 (next read three phases later)
# speedup vs baseline: 1.0276x; 1.0013x over previous
.LBB0_536:
	v_lshlrev_b32_e32 v177, 16, v168
	v_and_b32_e32 v179, 0xffff0000, v168
	v_and_b32_e32 v178, 0xffff0000, v166
	v_lshlrev_b32_e32 v181, 16, v169
	v_and_b32_e32 v169, 0xffff0000, v169
	v_and_b32_e32 v168, 0xffff0000, v167
	v_lshlrev_b32_e32 v176, 16, v166
	v_lshlrev_b32_e32 v180, 16, v167
	v_pk_mul_f32 v[192:193], v[178:179], v[178:179]
	v_pk_mul_f32 v[194:195], v[168:169], v[168:169]
	v_pk_fma_f32 v[192:193], v[176:177], v[176:177], v[192:193]
	v_pk_fma_f32 v[194:195], v[180:181], v[180:181], v[194:195]
	v_lshlrev_b32_e32 v167, 16, v165
	v_lshlrev_b32_e32 v166, 16, v164
	v_and_b32_e32 v165, 0xffff0000, v165
	v_and_b32_e32 v164, 0xffff0000, v164
	v_pk_add_f32 v[192:193], v[192:193], v[194:195]
	v_lshlrev_b32_e32 v182, 16, v162
	v_and_b32_e32 v183, 0xffff0000, v162
	v_lshlrev_b32_e32 v162, 16, v163
	v_lshlrev_b32_e32 v184, 16, v160
	v_pk_add_f32 v[192:193], v[192:193], v[192:193] op_sel_hi:[0,1]
	v_pk_mul_f32 v[194:195], v[164:165], v[164:165]
	v_and_b32_e32 v163, 0xffff0000, v163
	v_pk_fma_f32 v[194:195], v[166:167], v[166:167], v[194:195]
	v_mul_f32_e32 v185, v182, v182
	v_mul_f32_e32 v197, v183, v183
	v_mul_f32_e32 v192, v162, v162
	v_mov_b32_e32 v196, v184
	v_and_b32_e32 v202, 0xffff0000, v160
	v_lshlrev_b32_e32 v160, 16, v161
	v_and_b32_e32 v161, 0xffff0000, v161
	v_pk_add_f32 v[194:195], v[194:195], v[194:195] op_sel_hi:[0,1]
	v_pk_fma_f32 v[198:199], v[162:163], v[162:163], v[192:193] op_sel_hi:[1,1,0]
	v_pk_add_f32 v[196:197], v[184:185], v[196:197]
	v_mul_f32_e32 v198, v202, v202
	v_mul_f32_e32 v194, v160, v160
	v_mul_f32_e32 v192, v161, v161
	v_mul_f32_e32 v200, v184, v184
	v_mov_b32_e32 v201, v197
	v_pk_add_f32 v[196:197], v[200:201], v[198:199]
	v_pk_add_f32 v[192:193], v[194:195], v[192:193]
	v_lshlrev_b32_e32 v187, 16, v159
	v_lshlrev_b32_e32 v186, 16, v158
	v_and_b32_e32 v159, 0xffff0000, v159
	v_and_b32_e32 v158, 0xffff0000, v158
	v_pk_add_f32 v[192:193], v[196:197], v[192:193]
	v_lshlrev_b32_e32 v188, 16, v156
	v_and_b32_e32 v189, 0xffff0000, v156
	v_lshlrev_b32_e32 v156, 16, v157
	v_lshlrev_b32_e32 v190, 16, v154
	v_pk_add_f32 v[192:193], v[192:193], v[192:193] op_sel_hi:[0,1]
	v_pk_mul_f32 v[194:195], v[158:159], v[158:159]
	v_and_b32_e32 v157, 0xffff0000, v157
	v_pk_fma_f32 v[194:195], v[186:187], v[186:187], v[194:195]
	v_mul_f32_e32 v191, v188, v188
	v_mul_f32_e32 v197, v189, v189
	v_mul_f32_e32 v192, v156, v156
	v_mov_b32_e32 v196, v190
	v_and_b32_e32 v203, 0xffff0000, v154
	v_lshlrev_b32_e32 v154, 16, v155
	v_and_b32_e32 v155, 0xffff0000, v155
	v_pk_add_f32 v[194:195], v[194:195], v[194:195] op_sel_hi:[0,1]
	v_pk_fma_f32 v[198:199], v[156:157], v[156:157], v[192:193] op_sel_hi:[1,1,0]
	v_pk_add_f32 v[196:197], v[190:191], v[196:197]
	v_mul_f32_e32 v198, v203, v203
	v_mul_f32_e32 v194, v154, v154
	v_mul_f32_e32 v192, v155, v155
	v_mul_f32_e32 v200, v190, v190
	v_mov_b32_e32 v201, v197
	v_pk_add_f32 v[196:197], v[200:201], v[198:199]
	v_pk_add_f32 v[192:193], v[194:195], v[192:193]
	v_mov_b32_e32 v194, v177
	v_pk_add_f32 v[192:193], v[196:197], v[192:193]
	v_mov_b32_e32 v195, v179
	v_add_f32_e32 v185, v192, v193
	ds_bpermute_b32 v191, v170, v185
	v_mov_b32_e32 v177, v178
	v_mov_b32_e32 v196, v181
	v_mov_b32_e32 v197, v169
	v_mov_b32_e32 v181, v168
	s_waitcnt lgkmcnt(0)
	v_add_f32_e32 v185, v185, v191
	ds_bpermute_b32 v191, v171, v185
	s_add_i32 s28, s28, s64
	s_add_u32 s8, s8, s64
	s_addc_u32 s9, s9, s65
	s_add_u32 s12, s12, s20
	s_waitcnt lgkmcnt(0)
	v_add_f32_e32 v185, v185, v191
	ds_bpermute_b32 v191, v172, v185
	s_addc_u32 s13, s13, s21
	s_cmpk_lt_i32 s28, 0x2200
	s_waitcnt lgkmcnt(0)
	v_add_f32_e32 v185, v185, v191
	ds_bpermute_b32 v191, v173, v185
	s_waitcnt lgkmcnt(0)
	v_add_f32_e32 v185, v185, v191
	ds_bpermute_b32 v191, v174, v185
	s_waitcnt lgkmcnt(0)
	v_add_f32_e32 v185, v185, v191
	ds_bpermute_b32 v191, v175, v185
	s_waitcnt lgkmcnt(0)
	v_add_f32_e32 v185, v185, v191
	v_fmamk_f32 v185, v185, 0x3a000000, v1
	v_mul_f32_e32 v191, 0x4b800000, v185
	v_cmp_gt_f32_e32 vcc, s3, v185
	s_nop 1
	v_cndmask_b32_e32 v185, v185, v191, vcc
	v_rsq_f32_e32 v185, v185
	s_nop 0
	v_mul_f32_e32 v191, 0x45800000, v185
	v_cndmask_b32_e32 v192, v185, v191, vcc
	v_pk_mul_f32 v[160:161], v[192:193], v[160:161] op_sel_hi:[0,1]
	v_pk_mul_f32 v[194:195], v[192:193], v[194:195] op_sel_hi:[0,1]
	v_pk_mul_f32 v[176:177], v[192:193], v[176:177] op_sel_hi:[0,1]
	v_pk_fma_f32 v[112:113], v[36:37], v[160:161], v[112:113]
	v_mov_b32_e32 v161, v158
	v_mov_b32_e32 v158, v187
	v_pk_mul_f32 v[156:157], v[192:193], v[156:157] op_sel_hi:[0,1]
	v_mov_b32_e32 v191, v203
	v_pk_mul_f32 v[196:197], v[192:193], v[196:197] op_sel_hi:[0,1]
	v_pk_fma_f32 v[126:127], v[2:3], v[194:195], v[126:127]
	v_pk_mul_f32 v[168:169], v[192:193], v[180:181] op_sel_hi:[0,1]
	v_pk_fma_f32 v[122:123], v[10:11], v[176:177], v[122:123]
	v_pk_mul_f32 v[158:159], v[192:193], v[158:159] op_sel_hi:[0,1]
	v_pk_fma_f32 v[104:105], v[52:53], v[156:157], v[104:105]
	v_pk_mul_f32 v[156:157], v[192:193], v[190:191] op_sel_hi:[0,1]
	v_pk_fma_f32 v[128:129], v[4:5], v[196:197], v[128:129]
	v_pk_fma_f32 v[124:125], v[12:13], v[168:169], v[124:125]
	v_pk_fma_f32 v[108:109], v[40:41], v[158:159], v[108:109]
	v_pk_mul_f32 v[158:159], v[192:193], v[188:189] op_sel_hi:[0,1]
	v_pk_mul_f32 v[154:155], v[192:193], v[154:155] op_sel_hi:[0,1]
	v_pk_fma_f32 v[98:99], v[54:55], v[156:157], v[98:99]
	v_mov_b32_e32 v156, v127
	v_mov_b32_e32 v157, v123
	v_pk_fma_f32 v[102:103], v[50:51], v[158:159], v[102:103]
	v_pk_fma_f32 v[100:101], v[56:57], v[154:155], v[100:101]
	v_mov_b32_e32 v154, v126
	v_mov_b32_e32 v155, v122
	v_pk_mul_f32 v[156:157], v[156:157], v[156:157]
	v_mov_b32_e32 v158, v129
	v_mov_b32_e32 v159, v125
	v_mov_b32_e32 v168, v166
	v_mov_b32_e32 v169, v164
	v_mov_b32_e32 v164, v167
	v_pk_fma_f32 v[154:155], v[154:155], v[154:155], v[156:157]
	v_mov_b32_e32 v156, v128
	v_mov_b32_e32 v157, v124
	v_pk_mul_f32 v[158:159], v[158:159], v[158:159]
	v_pk_mul_f32 v[168:169], v[192:193], v[168:169] op_sel_hi:[0,1]
	v_pk_mul_f32 v[164:165], v[192:193], v[164:165] op_sel_hi:[0,1]
	v_pk_fma_f32 v[156:157], v[156:157], v[156:157], v[158:159]
	v_pk_fma_f32 v[120:121], v[20:21], v[164:165], v[120:121]
	v_pk_fma_f32 v[118:119], v[18:19], v[168:169], v[118:119]
	v_pk_mul_f32 v[164:165], v[192:193], v[182:183] op_sel_hi:[0,1]
	v_mov_b32_e32 v160, v186
	v_pk_add_f32 v[154:155], v[154:155], v[156:157]
	v_pk_mul_f32 v[162:163], v[192:193], v[162:163] op_sel_hi:[0,1]
	v_pk_fma_f32 v[114:115], v[26:27], v[164:165], v[114:115]
	v_pk_mul_f32 v[160:161], v[192:193], v[160:161] op_sel_hi:[0,1]
	v_pk_add_f32 v[154:155], v[154:155], v[154:155] op_sel_hi:[0,1]
	v_pk_mul_f32 v[156:157], v[120:121], v[120:121]
	v_pk_mul_f32 v[158:159], v[118:119], v[118:119]
	v_pk_fma_f32 v[116:117], v[28:29], v[162:163], v[116:117]
	v_mov_b32_e32 v185, v202
	v_pk_fma_f32 v[106:107], v[38:39], v[160:161], v[106:107]
	v_pk_mov_b32 v[160:161], v[158:159], v[156:157] op_sel:[1,0]
	v_mov_b32_e32 v159, v157
	v_mul_f32_e32 v154, v114, v114
	v_pk_mul_f32 v[162:163], v[192:193], v[184:185] op_sel_hi:[0,1]
	v_pk_add_f32 v[156:157], v[160:161], v[158:159]
	v_pk_fma_f32 v[158:159], v[114:115], v[114:115], v[154:155] op_sel_hi:[1,1,0]
	v_mul_f32_e32 v154, v116, v116
	v_pk_fma_f32 v[110:111], v[34:35], v[162:163], v[110:111]
	v_pk_add_f32 v[156:157], v[156:157], v[156:157] op_sel_hi:[0,1]
	v_pk_fma_f32 v[160:161], v[116:117], v[116:117], v[154:155] op_sel_hi:[1,1,0]
	v_mul_f32_e32 v158, v110, v110
	v_mul_f32_e32 v160, v111, v111
	v_mul_f32_e32 v156, v112, v112
	v_mul_f32_e32 v154, v113, v113
	v_pk_add_f32 v[158:159], v[158:159], v[160:161]
	v_pk_add_f32 v[154:155], v[156:157], v[154:155]
	v_pk_mul_f32 v[156:157], v[108:109], v[108:109]
	v_pk_add_f32 v[154:155], v[158:159], v[154:155]
	v_pk_mul_f32 v[158:159], v[106:107], v[106:107]
	v_pk_add_f32 v[154:155], v[154:155], v[154:155] op_sel_hi:[0,1]
	v_pk_mov_b32 v[160:161], v[158:159], v[156:157] op_sel:[1,0]
	v_mov_b32_e32 v159, v157
	v_mul_f32_e32 v154, v102, v102
	v_pk_add_f32 v[156:157], v[160:161], v[158:159]
	v_pk_fma_f32 v[158:159], v[102:103], v[102:103], v[154:155] op_sel_hi:[1,1,0]
	v_mul_f32_e32 v154, v104, v104
	v_pk_add_f32 v[156:157], v[156:157], v[156:157] op_sel_hi:[0,1]
	v_pk_fma_f32 v[160:161], v[104:105], v[104:105], v[154:155] op_sel_hi:[1,1,0]
	v_mul_f32_e32 v158, v98, v98
	v_mul_f32_e32 v160, v99, v99
	v_mul_f32_e32 v156, v100, v100
	v_mul_f32_e32 v154, v101, v101
	v_pk_add_f32 v[158:159], v[158:159], v[160:161]
	v_pk_add_f32 v[154:155], v[156:157], v[154:155]
	s_waitcnt vmcnt(3)
	v_mov_b64_e32 v[160:161], v[146:147]
	v_pk_add_f32 v[154:155], v[158:159], v[154:155]
	s_waitcnt vmcnt(2)
	v_mov_b64_e32 v[158:159], v[148:149]
	v_add_f32_e32 v155, v154, v155
	ds_bpermute_b32 v156, v170, v155
	v_cvt_pk_bf16_f32 v154, v126, v127
	v_mov_b64_e32 v[162:163], v[144:145]
	v_mov_b64_e32 v[164:165], v[140:141]
	v_mov_b64_e32 v[166:167], v[138:139]
	s_waitcnt lgkmcnt(0)
	v_add_f32_e32 v156, v155, v156
	ds_bpermute_b32 v157, v171, v156
	v_cvt_pk_bf16_f32 v155, v128, v129
	global_store_dwordx2 v[134:135], v[154:155], off nt
	v_cvt_pk_bf16_f32 v154, v122, v123
	v_cvt_pk_bf16_f32 v155, v124, v125
	s_waitcnt lgkmcnt(0)
	v_add_f32_e32 v156, v156, v157
	ds_bpermute_b32 v157, v172, v156
	global_store_dwordx2 v[134:135], v[154:155], off offset:512 nt
	v_cvt_pk_bf16_f32 v154, v118, v119
	v_cvt_pk_bf16_f32 v155, v120, v121
	global_store_dwordx2 v[134:135], v[154:155], off offset:1024 nt
	s_waitcnt lgkmcnt(0)
	v_add_f32_e32 v156, v156, v157
	ds_bpermute_b32 v157, v173, v156
	v_cvt_pk_bf16_f32 v154, v114, v115
	v_cvt_pk_bf16_f32 v155, v116, v117
	global_store_dwordx2 v[134:135], v[154:155], off offset:1536 nt
	v_cvt_pk_bf16_f32 v154, v110, v111
	s_waitcnt lgkmcnt(0)
	v_add_f32_e32 v156, v156, v157
	ds_bpermute_b32 v157, v174, v156
	v_cvt_pk_bf16_f32 v155, v112, v113
	global_store_dwordx2 v[134:135], v[154:155], off offset:2048 nt
	v_cvt_pk_bf16_f32 v154, v106, v107
	v_cvt_pk_bf16_f32 v155, v108, v109
	s_waitcnt lgkmcnt(0)
	v_add_f32_e32 v156, v156, v157
	ds_bpermute_b32 v157, v175, v156
	global_store_dwordx2 v[134:135], v[154:155], off offset:2560 nt
	v_cvt_pk_bf16_f32 v154, v102, v103
	v_cvt_pk_bf16_f32 v155, v104, v105
	global_store_dwordx2 v[134:135], v[154:155], off offset:3072 nt
	s_waitcnt lgkmcnt(0)
	v_add_f32_e32 v154, v156, v157
	v_fmamk_f32 v154, v154, 0x3a000000, v1
	v_mul_f32_e32 v155, 0x4b800000, v154
	v_cmp_gt_f32_e32 vcc, s3, v154
	v_mov_b64_e32 v[168:169], v[136:137]
	s_nop 0
	v_cndmask_b32_e32 v154, v154, v155, vcc
	v_rsq_f32_e32 v156, v154
	v_cvt_pk_bf16_f32 v154, v98, v99
	v_cvt_pk_bf16_f32 v155, v100, v101
	global_store_dwordx2 v[134:135], v[154:155], off offset:3584 nt
	v_mul_f32_e32 v154, 0x45800000, v156
	v_cndmask_b32_e32 v154, v156, v154, vcc
	v_pk_mul_f32 v[126:127], v[126:127], v[154:155] op_sel_hi:[1,0]
	v_pk_mul_f32 v[128:129], v[128:129], v[154:155] op_sel_hi:[1,0]
	v_pk_mul_f32 v[126:127], v[6:7], v[126:127]
	v_pk_mul_f32 v[128:129], v[8:9], v[128:129]
	v_cvt_pk_bf16_f32 v126, v126, v127
	v_cvt_pk_bf16_f32 v127, v128, v129
	v_add_co_u32_e32 v128, vcc, s26, v134
	v_pk_mul_f32 v[122:123], v[122:123], v[154:155] op_sel_hi:[1,0]
	v_pk_mul_f32 v[124:125], v[124:125], v[154:155] op_sel_hi:[1,0]
	v_addc_co_u32_e32 v129, vcc, -1, v135, vcc
	v_pk_mul_f32 v[124:125], v[16:17], v[124:125]
	v_pk_mul_f32 v[122:123], v[14:15], v[122:123]
	v_pk_mul_f32 v[118:119], v[118:119], v[154:155] op_sel_hi:[1,0]
	v_pk_mul_f32 v[120:121], v[120:121], v[154:155] op_sel_hi:[1,0]
	v_pk_mul_f32 v[114:115], v[114:115], v[154:155] op_sel_hi:[1,0]
	v_pk_mul_f32 v[116:117], v[116:117], v[154:155] op_sel_hi:[1,0]
	v_pk_mul_f32 v[110:111], v[110:111], v[154:155] op_sel_hi:[1,0]
	v_pk_mul_f32 v[112:113], v[112:113], v[154:155] op_sel_hi:[1,0]
	v_pk_mul_f32 v[106:107], v[106:107], v[154:155] op_sel_hi:[1,0]
	v_pk_mul_f32 v[108:109], v[108:109], v[154:155] op_sel_hi:[1,0]
	v_pk_mul_f32 v[102:103], v[102:103], v[154:155] op_sel_hi:[1,0]
	v_pk_mul_f32 v[104:105], v[104:105], v[154:155] op_sel_hi:[1,0]
	v_pk_mul_f32 v[98:99], v[98:99], v[154:155] op_sel_hi:[1,0]
	v_pk_mul_f32 v[100:101], v[100:101], v[154:155] op_sel_hi:[1,0]
	v_cvt_pk_bf16_f32 v122, v122, v123
	v_cvt_pk_bf16_f32 v123, v124, v125
	v_add_co_u32_e32 v124, vcc, s27, v134
	v_pk_mul_f32 v[120:121], v[24:25], v[120:121]
	v_pk_mul_f32 v[118:119], v[22:23], v[118:119]
	v_pk_mul_f32 v[116:117], v[32:33], v[116:117]
	v_pk_mul_f32 v[114:115], v[30:31], v[114:115]
	v_pk_mul_f32 v[112:113], v[44:45], v[112:113]
	v_pk_mul_f32 v[110:111], v[42:43], v[110:111]
	v_pk_mul_f32 v[108:109], v[48:49], v[108:109]
	v_pk_mul_f32 v[106:107], v[46:47], v[106:107]
	v_pk_mul_f32 v[104:105], v[60:61], v[104:105]
	v_pk_mul_f32 v[102:103], v[58:59], v[102:103]
	v_pk_mul_f32 v[100:101], v[64:65], v[100:101]
	v_pk_mul_f32 v[98:99], v[62:63], v[98:99]
	v_addc_co_u32_e32 v125, vcc, -1, v135, vcc
	v_cvt_pk_bf16_f32 v118, v118, v119
	v_cvt_pk_bf16_f32 v119, v120, v121
	v_cvt_pk_bf16_f32 v114, v114, v115
	v_cvt_pk_bf16_f32 v115, v116, v117
	v_cvt_pk_bf16_f32 v110, v110, v111
	v_cvt_pk_bf16_f32 v111, v112, v113
	v_cvt_pk_bf16_f32 v106, v106, v107
	v_cvt_pk_bf16_f32 v107, v108, v109
	v_cvt_pk_bf16_f32 v102, v102, v103
	v_cvt_pk_bf16_f32 v103, v104, v105
	v_cvt_pk_bf16_f32 v98, v98, v99
	v_cvt_pk_bf16_f32 v99, v100, v101
	global_store_dwordx2 v[128:129], v[126:127], off
	global_store_dwordx2 v[124:125], v[122:123], off offset:-3584
	global_store_dwordx2 v[124:125], v[118:119], off offset:-3072
	global_store_dwordx2 v[124:125], v[114:115], off offset:-2560
	global_store_dwordx2 v[124:125], v[110:111], off offset:-2048
	global_store_dwordx2 v[124:125], v[106:107], off offset:-1536
	global_store_dwordx2 v[124:125], v[102:103], off offset:-1024
	global_store_dwordx2 v[124:125], v[98:99], off offset:-512
	v_mov_b64_e32 v[128:129], v[80:81]
	v_mov_b64_e32 v[124:125], v[76:77]
	v_mov_b64_e32 v[120:121], v[72:73]
	v_mov_b64_e32 v[116:117], v[68:69]
	v_mov_b64_e32 v[112:113], v[96:97]
	v_mov_b64_e32 v[108:109], v[92:93]
	v_mov_b64_e32 v[104:105], v[88:89]
	v_mov_b64_e32 v[100:101], v[84:85]
	v_lshl_add_u64 v[134:135], v[134:135], 0, s[10:11]
	s_waitcnt vmcnt(16)
	v_mov_b64_e32 v[154:155], v[152:153]
	v_mov_b64_e32 v[156:157], v[150:151]
	v_mov_b64_e32 v[126:127], v[78:79]
	v_mov_b64_e32 v[122:123], v[74:75]
	v_mov_b64_e32 v[118:119], v[70:71]
	v_mov_b64_e32 v[114:115], v[66:67]
	v_mov_b64_e32 v[110:111], v[94:95]
	v_mov_b64_e32 v[106:107], v[90:91]
	v_mov_b64_e32 v[102:103], v[86:87]
	v_mov_b64_e32 v[98:99], v[82:83]
	s_cbranch_scc0 .LBB0_540

.LBB0_792:
	v_lshlrev_b32_e32 v177, 16, v162
	v_and_b32_e32 v179, 0xffff0000, v162
	v_and_b32_e32 v178, 0xffff0000, v160
	v_lshlrev_b32_e32 v181, 16, v163
	v_and_b32_e32 v163, 0xffff0000, v163
	v_and_b32_e32 v162, 0xffff0000, v161
	v_lshlrev_b32_e32 v176, 16, v160
	v_lshlrev_b32_e32 v180, 16, v161
	v_pk_mul_f32 v[192:193], v[178:179], v[178:179]
	v_pk_mul_f32 v[194:195], v[162:163], v[162:163]
	v_pk_fma_f32 v[192:193], v[176:177], v[176:177], v[192:193]
	v_pk_fma_f32 v[194:195], v[180:181], v[180:181], v[194:195]
	v_lshlrev_b32_e32 v161, 16, v159
	v_lshlrev_b32_e32 v160, 16, v158
	v_and_b32_e32 v159, 0xffff0000, v159
	v_and_b32_e32 v158, 0xffff0000, v158
	v_pk_add_f32 v[192:193], v[192:193], v[194:195]
	v_lshlrev_b32_e32 v182, 16, v156
	v_and_b32_e32 v183, 0xffff0000, v156
	v_lshlrev_b32_e32 v156, 16, v157
	v_lshlrev_b32_e32 v184, 16, v154
	v_pk_add_f32 v[192:193], v[192:193], v[192:193] op_sel_hi:[0,1]
	v_pk_mul_f32 v[194:195], v[158:159], v[158:159]
	v_and_b32_e32 v157, 0xffff0000, v157
	v_pk_fma_f32 v[194:195], v[160:161], v[160:161], v[194:195]
	v_mul_f32_e32 v185, v182, v182
	v_mul_f32_e32 v197, v183, v183
	v_mul_f32_e32 v192, v156, v156
	v_mov_b32_e32 v196, v184
	v_and_b32_e32 v211, 0xffff0000, v154
	v_lshlrev_b32_e32 v186, 16, v155
	v_and_b32_e32 v187, 0xffff0000, v155
	v_pk_add_f32 v[194:195], v[194:195], v[194:195] op_sel_hi:[0,1]
	v_pk_fma_f32 v[198:199], v[156:157], v[156:157], v[192:193] op_sel_hi:[1,1,0]
	v_pk_add_f32 v[196:197], v[184:185], v[196:197]
	v_mul_f32_e32 v198, v211, v211
	v_mul_f32_e32 v194, v186, v186
	v_mul_f32_e32 v192, v187, v187
	v_mul_f32_e32 v200, v184, v184
	v_mov_b32_e32 v201, v197
	v_pk_add_f32 v[196:197], v[200:201], v[198:199]
	v_pk_add_f32 v[192:193], v[194:195], v[192:193]
	v_and_b32_e32 v191, 0xffff0000, v153
	v_and_b32_e32 v190, 0xffff0000, v152
	v_pk_add_f32 v[192:193], v[196:197], v[192:193]
	v_lshlrev_b32_e32 v189, 16, v153
	v_lshlrev_b32_e32 v188, 16, v152
	v_lshlrev_b32_e32 v152, 16, v150
	v_and_b32_e32 v153, 0xffff0000, v150
	v_lshlrev_b32_e32 v154, 16, v151
	v_lshlrev_b32_e32 v150, 16, v148
	v_pk_add_f32 v[192:193], v[192:193], v[192:193] op_sel_hi:[0,1]
	v_pk_mul_f32 v[194:195], v[190:191], v[190:191]
	v_and_b32_e32 v155, 0xffff0000, v151
	v_pk_fma_f32 v[194:195], v[188:189], v[188:189], v[194:195]
	v_mul_f32_e32 v151, v152, v152
	v_mul_f32_e32 v197, v153, v153
	v_mul_f32_e32 v192, v154, v154
	v_mov_b32_e32 v196, v150
	v_and_b32_e32 v212, 0xffff0000, v148
	v_lshlrev_b32_e32 v148, 16, v149
	v_and_b32_e32 v149, 0xffff0000, v149
	v_pk_add_f32 v[194:195], v[194:195], v[194:195] op_sel_hi:[0,1]
	v_pk_fma_f32 v[198:199], v[154:155], v[154:155], v[192:193] op_sel_hi:[1,1,0]
	v_pk_add_f32 v[196:197], v[150:151], v[196:197]
	v_mul_f32_e32 v198, v212, v212
	v_mul_f32_e32 v194, v148, v148
	v_mul_f32_e32 v192, v149, v149
	v_mul_f32_e32 v200, v150, v150
	v_mov_b32_e32 v201, v197
	v_pk_add_f32 v[196:197], v[200:201], v[198:199]
	v_pk_add_f32 v[192:193], v[194:195], v[192:193]
	v_lshlrev_b32_e32 v198, 16, v136
	v_pk_add_f32 v[192:193], v[196:197], v[192:193]
	v_and_b32_e32 v199, 0xffff0000, v136
	v_add_f32_e32 v151, v192, v193
	ds_bpermute_b32 v185, v1, v151
	v_lshlrev_b32_e32 v200, 16, v137
	v_and_b32_e32 v201, 0xffff0000, v137
	v_lshlrev_b32_e32 v202, 16, v134
	v_and_b32_e32 v203, 0xffff0000, v134
	s_waitcnt lgkmcnt(0)
	v_add_f32_e32 v151, v151, v185
	ds_bpermute_b32 v185, v166, v151
	v_lshlrev_b32_e32 v204, 16, v135
	v_and_b32_e32 v205, 0xffff0000, v135
	v_lshlrev_b32_e32 v206, 16, v132
	v_and_b32_e32 v207, 0xffff0000, v132
	s_waitcnt lgkmcnt(0)
	v_add_f32_e32 v151, v151, v185
	ds_bpermute_b32 v185, v167, v151
	v_lshlrev_b32_e32 v208, 16, v133
	v_and_b32_e32 v209, 0xffff0000, v133
	v_mov_b32_e32 v133, v179
	v_lshlrev_b32_e32 v172, 16, v164
	s_waitcnt lgkmcnt(0)
	v_add_f32_e32 v151, v151, v185
	ds_bpermute_b32 v185, v168, v151
	v_and_b32_e32 v173, 0xffff0000, v164
	v_lshlrev_b32_e32 v164, 16, v165
	v_and_b32_e32 v165, 0xffff0000, v165
	v_lshlrev_b32_e32 v174, 16, v146
	s_waitcnt lgkmcnt(0)
	v_add_f32_e32 v151, v151, v185
	ds_bpermute_b32 v185, v169, v151
	v_and_b32_e32 v175, 0xffff0000, v146
	v_lshlrev_b32_e32 v146, 16, v147
	v_and_b32_e32 v147, 0xffff0000, v147
	v_lshlrev_b32_e32 v192, 16, v144
	s_waitcnt lgkmcnt(0)
	v_add_f32_e32 v136, v151, v185
	ds_bpermute_b32 v137, v170, v136
	v_and_b32_e32 v193, 0xffff0000, v144
	v_lshlrev_b32_e32 v144, 16, v145
	v_and_b32_e32 v145, 0xffff0000, v145
	v_lshlrev_b32_e32 v194, 16, v140
	s_waitcnt lgkmcnt(0)
	v_add_f32_e32 v134, v136, v137
	v_fmamk_f32 v134, v134, 0x3a000000, v171
	v_mul_f32_e32 v135, 0x4b800000, v134
	v_cmp_gt_f32_e32 vcc, s12, v134
	v_and_b32_e32 v195, 0xffff0000, v140
	v_lshlrev_b32_e32 v140, 16, v141
	v_cndmask_b32_e32 v134, v134, v135, vcc
	v_rsq_f32_e32 v134, v134
	v_and_b32_e32 v141, 0xffff0000, v141
	v_mov_b32_e32 v185, v211
	v_lshlrev_b32_e32 v196, 16, v138
	v_mul_f32_e32 v132, 0x45800000, v134
	v_cndmask_b32_e32 v210, v134, v132, vcc
	v_mov_b32_e32 v132, v177
	v_pk_mul_f32 v[134:135], v[210:211], v[132:133] op_sel_hi:[0,1]
	v_mov_b32_e32 v132, v181
	v_mov_b32_e32 v133, v163
	v_pk_mul_f32 v[132:133], v[210:211], v[132:133] op_sel_hi:[0,1]
	v_mov_b32_e32 v177, v178
	v_mov_b32_e32 v181, v162
	v_pk_fma_f32 v[132:133], v[4:5], v[132:133], v[164:165]
	v_pk_mul_f32 v[164:165], v[210:211], v[176:177] op_sel_hi:[0,1]
	v_pk_mul_f32 v[136:137], v[210:211], v[180:181] op_sel_hi:[0,1]
	v_pk_fma_f32 v[134:135], v[2:3], v[134:135], v[172:173]
	v_pk_fma_f32 v[136:137], v[12:13], v[136:137], v[146:147]
	v_pk_fma_f32 v[146:147], v[10:11], v[164:165], v[174:175]
	v_mov_b32_e32 v174, v135
	v_mov_b32_e32 v175, v147
	v_mov_b32_e32 v172, v134
	v_mov_b32_e32 v173, v146
	v_pk_mul_f32 v[174:175], v[174:175], v[174:175]
	v_mov_b32_e32 v176, v133
	v_mov_b32_e32 v177, v137
	v_mov_b32_e32 v162, v160
	v_mov_b32_e32 v163, v158
	v_mov_b32_e32 v158, v161
	v_pk_fma_f32 v[172:173], v[172:173], v[172:173], v[174:175]
	v_mov_b32_e32 v174, v132
	v_mov_b32_e32 v175, v136
	v_pk_mul_f32 v[176:177], v[176:177], v[176:177]
	v_pk_mul_f32 v[162:163], v[210:211], v[162:163] op_sel_hi:[0,1]
	v_pk_mul_f32 v[158:159], v[210:211], v[158:159] op_sel_hi:[0,1]
	v_pk_fma_f32 v[174:175], v[174:175], v[174:175], v[176:177]
	v_pk_fma_f32 v[144:145], v[28:29], v[158:159], v[144:145]
	v_pk_fma_f32 v[158:159], v[26:27], v[162:163], v[192:193]
	v_pk_mul_f32 v[160:161], v[210:211], v[182:183] op_sel_hi:[0,1]
	v_pk_mul_f32 v[156:157], v[210:211], v[156:157] op_sel_hi:[0,1]
	v_pk_add_f32 v[172:173], v[172:173], v[174:175]
	v_pk_fma_f32 v[140:141], v[44:45], v[156:157], v[140:141]
	v_pk_fma_f32 v[156:157], v[42:43], v[160:161], v[194:195]
	v_pk_add_f32 v[172:173], v[172:173], v[172:173] op_sel_hi:[0,1]
	v_pk_mul_f32 v[174:175], v[144:145], v[144:145]
	v_pk_mul_f32 v[176:177], v[158:159], v[158:159]
	v_mul_f32_e32 v172, v156, v156
	v_pk_mov_b32 v[178:179], v[176:177], v[174:175] op_sel:[1,0]
	v_mov_b32_e32 v177, v175
	v_and_b32_e32 v197, 0xffff0000, v138
	v_lshlrev_b32_e32 v138, 16, v139
	v_and_b32_e32 v139, 0xffff0000, v139
	v_pk_mul_f32 v[160:161], v[210:211], v[184:185] op_sel_hi:[0,1]
	v_pk_mul_f32 v[162:163], v[210:211], v[186:187] op_sel_hi:[0,1]
	v_pk_add_f32 v[174:175], v[178:179], v[176:177]
	v_pk_fma_f32 v[176:177], v[156:157], v[156:157], v[172:173] op_sel_hi:[1,1,0]
	v_mul_f32_e32 v172, v140, v140
	v_pk_fma_f32 v[138:139], v[52:53], v[162:163], v[138:139]
	v_pk_fma_f32 v[160:161], v[50:51], v[160:161], v[196:197]
	v_pk_add_f32 v[174:175], v[174:175], v[174:175] op_sel_hi:[0,1]
	v_pk_fma_f32 v[178:179], v[140:141], v[140:141], v[172:173] op_sel_hi:[1,1,0]
	v_mov_b32_e32 v162, v188
	v_mov_b32_e32 v163, v190
	v_mov_b32_e32 v190, v189
	v_mul_f32_e32 v176, v160, v160
	v_mul_f32_e32 v178, v161, v161
	v_mul_f32_e32 v174, v138, v138
	v_mul_f32_e32 v172, v139, v139
	v_pk_mul_f32 v[162:163], v[210:211], v[162:163] op_sel_hi:[0,1]
	v_pk_mul_f32 v[164:165], v[210:211], v[190:191] op_sel_hi:[0,1]
	v_pk_add_f32 v[176:177], v[176:177], v[178:179]
	v_pk_add_f32 v[172:173], v[174:175], v[172:173]
	v_pk_fma_f32 v[164:165], v[56:57], v[164:165], v[200:201]
	v_pk_fma_f32 v[162:163], v[54:55], v[162:163], v[198:199]
	v_pk_mul_f32 v[152:153], v[210:211], v[152:153] op_sel_hi:[0,1]
	v_pk_add_f32 v[172:173], v[176:177], v[172:173]
	v_pk_mul_f32 v[154:155], v[210:211], v[154:155] op_sel_hi:[0,1]
	v_pk_fma_f32 v[152:153], v[74:75], v[152:153], v[202:203]
	v_pk_add_f32 v[172:173], v[172:173], v[172:173] op_sel_hi:[0,1]
	v_pk_mul_f32 v[174:175], v[164:165], v[164:165]
	v_pk_mul_f32 v[176:177], v[162:163], v[162:163]
	v_pk_fma_f32 v[154:155], v[76:77], v[154:155], v[204:205]
	v_mov_b32_e32 v151, v212
	v_pk_mov_b32 v[178:179], v[176:177], v[174:175] op_sel:[1,0]
	v_mov_b32_e32 v177, v175
	v_mul_f32_e32 v172, v152, v152
	v_pk_mul_f32 v[150:151], v[210:211], v[150:151] op_sel_hi:[0,1]
	v_pk_mul_f32 v[148:149], v[210:211], v[148:149] op_sel_hi:[0,1]
	v_pk_add_f32 v[174:175], v[178:179], v[176:177]
	v_pk_fma_f32 v[176:177], v[152:153], v[152:153], v[172:173] op_sel_hi:[1,1,0]
	v_mul_f32_e32 v172, v154, v154
	v_pk_fma_f32 v[148:149], v[80:81], v[148:149], v[208:209]
	v_pk_fma_f32 v[150:151], v[78:79], v[150:151], v[206:207]
	v_pk_add_f32 v[174:175], v[174:175], v[174:175] op_sel_hi:[0,1]
	v_pk_fma_f32 v[178:179], v[154:155], v[154:155], v[172:173] op_sel_hi:[1,1,0]
	v_mul_f32_e32 v176, v150, v150
	v_mul_f32_e32 v178, v151, v151
	v_mul_f32_e32 v174, v148, v148
	v_mul_f32_e32 v172, v149, v149
	v_pk_add_f32 v[176:177], v[176:177], v[178:179]
	v_pk_add_f32 v[172:173], v[174:175], v[172:173]
	v_cvt_pk_bf16_f32 v174, v134, v135
	v_pk_add_f32 v[172:173], v[176:177], v[172:173]
	v_cvt_pk_bf16_f32 v175, v132, v133
	v_add_f32_e32 v176, v172, v173
	ds_bpermute_b32 v177, v1, v176
	v_lshl_add_u64 v[172:173], s[4:5], 0, v[98:99]
	s_add_u32 s4, s4, s6
	s_addc_u32 s5, s5, s7
	s_add_u32 s8, s8, s6
	s_waitcnt lgkmcnt(0)
	v_add_f32_e32 v178, v176, v177
	ds_bpermute_b32 v179, v166, v178
	v_add_co_u32_e32 v176, vcc, s3, v172
	s_addc_u32 s9, s9, s7
	s_nop 0
	v_addc_co_u32_e32 v177, vcc, 0, v173, vcc
	s_waitcnt lgkmcnt(0)
	v_add_f32_e32 v178, v178, v179
	ds_bpermute_b32 v179, v167, v178
	global_store_dwordx2 v[176:177], v[174:175], off nt
	v_cvt_pk_bf16_f32 v174, v146, v147
	v_cvt_pk_bf16_f32 v175, v136, v137
	global_store_dwordx2 v[176:177], v[174:175], off offset:512 nt
	s_waitcnt lgkmcnt(0)
	v_add_f32_e32 v178, v178, v179
	ds_bpermute_b32 v179, v168, v178
	v_cvt_pk_bf16_f32 v174, v158, v159
	v_cvt_pk_bf16_f32 v175, v144, v145
	global_store_dwordx2 v[176:177], v[174:175], off offset:1024 nt
	v_cvt_pk_bf16_f32 v174, v156, v157
	s_waitcnt lgkmcnt(0)
	v_add_f32_e32 v178, v178, v179
	ds_bpermute_b32 v179, v169, v178
	v_cvt_pk_bf16_f32 v175, v140, v141
	global_store_dwordx2 v[176:177], v[174:175], off offset:1536 nt
	v_cvt_pk_bf16_f32 v174, v160, v161
	v_cvt_pk_bf16_f32 v175, v138, v139
	s_waitcnt lgkmcnt(0)
	v_add_f32_e32 v178, v178, v179
	ds_bpermute_b32 v179, v170, v178
	global_store_dwordx2 v[176:177], v[174:175], off offset:2048 nt
	v_cvt_pk_bf16_f32 v174, v162, v163
	v_cvt_pk_bf16_f32 v175, v164, v165
	global_store_dwordx2 v[176:177], v[174:175], off offset:2560 nt
	v_cvt_pk_bf16_f32 v174, v152, v153
	v_cvt_pk_bf16_f32 v175, v154, v155
	global_store_dwordx2 v[176:177], v[174:175], off offset:3072 nt
	s_waitcnt lgkmcnt(0)
	v_add_f32_e32 v174, v178, v179
	v_fmamk_f32 v174, v174, 0x3a000000, v171
	v_mul_f32_e32 v175, 0x4b800000, v174
	v_cmp_gt_f32_e32 vcc, s12, v174
	s_nop 1
	v_cndmask_b32_e32 v174, v174, v175, vcc
	v_rsq_f32_e32 v178, v174
	v_cvt_pk_bf16_f32 v174, v150, v151
	v_cvt_pk_bf16_f32 v175, v148, v149
	global_store_dwordx2 v[176:177], v[174:175], off offset:3584 nt
	v_mul_f32_e32 v174, 0x45800000, v178
	v_cndmask_b32_e32 v174, v178, v174, vcc
	v_pk_mul_f32 v[134:135], v[134:135], v[174:175] op_sel_hi:[1,0]
	v_pk_mul_f32 v[132:133], v[132:133], v[174:175] op_sel_hi:[1,0]
	v_pk_mul_f32 v[178:179], v[34:35], v[134:135]
	v_pk_mul_f32 v[176:177], v[36:37], v[132:133]
	v_cvt_pk_bf16_f32 v178, v178, v179
	v_cvt_pk_bf16_f32 v179, v176, v177
	v_add_co_u32_e32 v176, vcc, s13, v172
	v_pk_mul_f32 v[132:133], v[8:9], v[132:133]
	s_nop 0
	v_addc_co_u32_e32 v177, vcc, 0, v173, vcc
	v_pk_mul_f32 v[134:135], v[6:7], v[134:135]
	v_pk_mul_f32 v[146:147], v[146:147], v[174:175] op_sel_hi:[1,0]
	v_cvt_pk_bf16_f32 v134, v134, v135
	v_cvt_pk_bf16_f32 v135, v132, v133
	v_add_co_u32_e32 v132, vcc, s18, v172
	v_pk_mul_f32 v[136:137], v[136:137], v[174:175] op_sel_hi:[1,0]
	s_nop 0
	v_addc_co_u32_e32 v133, vcc, 0, v173, vcc
	global_store_dwordx2 v[176:177], v[178:179], off
	v_pk_mul_f32 v[178:179], v[20:21], v[136:137]
	global_store_dwordx2 v[132:133], v[134:135], off
	v_pk_mul_f32 v[134:135], v[16:17], v[136:137]
	v_pk_mul_f32 v[136:137], v[14:15], v[146:147]
	v_pk_mul_f32 v[158:159], v[158:159], v[174:175] op_sel_hi:[1,0]
	v_pk_mul_f32 v[144:145], v[144:145], v[174:175] op_sel_hi:[1,0]
	v_cvt_pk_bf16_f32 v136, v136, v137
	v_cvt_pk_bf16_f32 v137, v134, v135
	v_pk_mul_f32 v[180:181], v[18:19], v[146:147]
	global_store_dwordx2 v[132:133], v[136:137], off offset:512
	v_pk_mul_f32 v[134:135], v[32:33], v[144:145]
	v_pk_mul_f32 v[136:137], v[30:31], v[158:159]
	v_cvt_pk_bf16_f32 v180, v180, v181
	v_cvt_pk_bf16_f32 v181, v178, v179
	v_pk_mul_f32 v[156:157], v[156:157], v[174:175] op_sel_hi:[1,0]
	v_pk_mul_f32 v[140:141], v[140:141], v[174:175] op_sel_hi:[1,0]
	v_cvt_pk_bf16_f32 v136, v136, v137
	v_cvt_pk_bf16_f32 v137, v134, v135
	global_store_dwordx2 v[176:177], v[180:181], off offset:512
	v_pk_mul_f32 v[178:179], v[24:25], v[144:145]
	v_pk_mul_f32 v[180:181], v[22:23], v[158:159]
	global_store_dwordx2 v[132:133], v[136:137], off offset:1024
	v_pk_mul_f32 v[134:135], v[48:49], v[140:141]
	v_pk_mul_f32 v[136:137], v[46:47], v[156:157]
	v_cvt_pk_bf16_f32 v180, v180, v181
	v_cvt_pk_bf16_f32 v181, v178, v179
	v_pk_mul_f32 v[160:161], v[160:161], v[174:175] op_sel_hi:[1,0]
	v_pk_mul_f32 v[138:139], v[138:139], v[174:175] op_sel_hi:[1,0]
	v_cvt_pk_bf16_f32 v136, v136, v137
	v_cvt_pk_bf16_f32 v137, v134, v135
	global_store_dwordx2 v[176:177], v[180:181], off offset:1024
	v_pk_mul_f32 v[178:179], v[40:41], v[140:141]
	v_pk_mul_f32 v[180:181], v[38:39], v[156:157]
	global_store_dwordx2 v[132:133], v[136:137], off offset:1536
	v_pk_mul_f32 v[134:135], v[68:69], v[138:139]
	v_pk_mul_f32 v[136:137], v[66:67], v[160:161]
	v_cvt_pk_bf16_f32 v180, v180, v181
	v_cvt_pk_bf16_f32 v181, v178, v179
	v_pk_mul_f32 v[162:163], v[162:163], v[174:175] op_sel_hi:[1,0]
	v_pk_mul_f32 v[164:165], v[164:165], v[174:175] op_sel_hi:[1,0]
	v_cvt_pk_bf16_f32 v136, v136, v137
	v_cvt_pk_bf16_f32 v137, v134, v135
	global_store_dwordx2 v[176:177], v[180:181], off offset:1536
	v_pk_mul_f32 v[178:179], v[60:61], v[138:139]
	v_pk_mul_f32 v[180:181], v[58:59], v[160:161]
	global_store_dwordx2 v[132:133], v[136:137], off offset:2048
	v_pk_mul_f32 v[134:135], v[72:73], v[164:165]
	v_pk_mul_f32 v[136:137], v[70:71], v[162:163]
	v_cvt_pk_bf16_f32 v180, v180, v181
	v_cvt_pk_bf16_f32 v181, v178, v179
	v_pk_mul_f32 v[152:153], v[152:153], v[174:175] op_sel_hi:[1,0]
	v_pk_mul_f32 v[154:155], v[154:155], v[174:175] op_sel_hi:[1,0]
	v_cvt_pk_bf16_f32 v136, v136, v137
	v_cvt_pk_bf16_f32 v137, v134, v135
	global_store_dwordx2 v[176:177], v[180:181], off offset:2048
	v_pk_mul_f32 v[178:179], v[64:65], v[164:165]
	v_pk_mul_f32 v[180:181], v[62:63], v[162:163]
	global_store_dwordx2 v[132:133], v[136:137], off offset:2560
	s_waitcnt vmcnt(20)
	v_pk_mul_f32 v[134:135], v[92:93], v[154:155]
	v_pk_mul_f32 v[136:137], v[90:91], v[152:153]
	v_cvt_pk_bf16_f32 v180, v180, v181
	v_cvt_pk_bf16_f32 v181, v178, v179
	v_pk_mul_f32 v[150:151], v[150:151], v[174:175] op_sel_hi:[1,0]
	v_pk_mul_f32 v[148:149], v[148:149], v[174:175] op_sel_hi:[1,0]
	v_cvt_pk_bf16_f32 v136, v136, v137
	v_cvt_pk_bf16_f32 v137, v134, v135
	global_store_dwordx2 v[176:177], v[180:181], off offset:2560
	v_pk_mul_f32 v[178:179], v[84:85], v[154:155]
	v_pk_mul_f32 v[180:181], v[82:83], v[152:153]
	global_store_dwordx2 v[132:133], v[136:137], off offset:3072
	s_waitcnt vmcnt(21)
	v_pk_mul_f32 v[134:135], v[96:97], v[148:149]
	v_pk_mul_f32 v[136:137], v[94:95], v[150:151]
	v_cvt_pk_bf16_f32 v180, v180, v181
	v_cvt_pk_bf16_f32 v181, v178, v179
	v_pk_mul_f32 v[174:175], v[88:89], v[148:149]
	v_pk_mul_f32 v[178:179], v[86:87], v[150:151]
	v_cvt_pk_bf16_f32 v136, v136, v137
	v_cvt_pk_bf16_f32 v137, v134, v135
	v_cvt_pk_bf16_f32 v178, v178, v179
	v_cvt_pk_bf16_f32 v179, v174, v175
	global_store_dwordx2 v[132:133], v[136:137], off offset:3584
	s_andn2_b64 vcc, exec, s[10:11]
	v_mov_b64_e32 v[148:149], v[112:113]
	v_mov_b64_e32 v[150:151], v[114:115]
	v_mov_b64_e32 v[152:153], v[116:117]
	v_mov_b64_e32 v[154:155], v[118:119]
	v_mov_b64_e32 v[156:157], v[120:121]
	v_mov_b64_e32 v[158:159], v[122:123]
	v_mov_b64_e32 v[160:161], v[124:125]
	v_mov_b64_e32 v[162:163], v[126:127]
	v_mov_b64_e32 v[164:165], v[100:101]
	v_mov_b64_e32 v[146:147], v[102:103]
	v_mov_b64_e32 v[144:145], v[104:105]
	v_mov_b64_e32 v[140:141], v[106:107]
	v_mov_b64_e32 v[138:139], v[108:109]
	v_mov_b64_e32 v[136:137], v[110:111]
	v_mov_b64_e32 v[134:135], v[128:129]
	v_mov_b64_e32 v[132:133], v[130:131]
	global_store_dwordx2 v[176:177], v[180:181], off offset:3072
	global_store_dwordx2 v[176:177], v[178:179], off offset:3584
	s_cbranch_vccz .LBB0_795

.LBB0_1349:
	v_lshlrev_b32_e32 v145, 16, v128
	v_and_b32_e32 v147, 0xffff0000, v128
	v_and_b32_e32 v146, 0xffff0000, v126
	v_lshlrev_b32_e32 v149, 16, v129
	v_and_b32_e32 v129, 0xffff0000, v129
	v_and_b32_e32 v128, 0xffff0000, v127
	v_lshlrev_b32_e32 v144, 16, v126
	v_lshlrev_b32_e32 v148, 16, v127
	v_pk_mul_f32 v[160:161], v[146:147], v[146:147]
	v_pk_mul_f32 v[162:163], v[128:129], v[128:129]
	v_pk_fma_f32 v[160:161], v[144:145], v[144:145], v[160:161]
	v_pk_fma_f32 v[162:163], v[148:149], v[148:149], v[162:163]
	v_lshlrev_b32_e32 v127, 16, v125
	v_lshlrev_b32_e32 v126, 16, v124
	v_and_b32_e32 v125, 0xffff0000, v125
	v_and_b32_e32 v124, 0xffff0000, v124
	v_pk_add_f32 v[160:161], v[160:161], v[162:163]
	v_lshlrev_b32_e32 v150, 16, v122
	v_and_b32_e32 v151, 0xffff0000, v122
	v_lshlrev_b32_e32 v122, 16, v123
	v_lshlrev_b32_e32 v152, 16, v120
	v_pk_add_f32 v[160:161], v[160:161], v[160:161] op_sel_hi:[0,1]
	v_pk_mul_f32 v[162:163], v[124:125], v[124:125]
	v_and_b32_e32 v123, 0xffff0000, v123
	v_pk_fma_f32 v[162:163], v[126:127], v[126:127], v[162:163]
	v_mul_f32_e32 v153, v150, v150
	v_mul_f32_e32 v165, v151, v151
	v_mul_f32_e32 v160, v122, v122
	v_mov_b32_e32 v164, v152
	v_and_b32_e32 v179, 0xffff0000, v120
	v_lshlrev_b32_e32 v154, 16, v121
	v_and_b32_e32 v155, 0xffff0000, v121
	v_pk_add_f32 v[162:163], v[162:163], v[162:163] op_sel_hi:[0,1]
	v_pk_fma_f32 v[166:167], v[122:123], v[122:123], v[160:161] op_sel_hi:[1,1,0]
	v_pk_add_f32 v[164:165], v[152:153], v[164:165]
	v_mul_f32_e32 v166, v179, v179
	v_mul_f32_e32 v162, v154, v154
	v_mul_f32_e32 v160, v155, v155
	v_mul_f32_e32 v168, v152, v152
	v_mov_b32_e32 v169, v165
	v_pk_add_f32 v[164:165], v[168:169], v[166:167]
	v_pk_add_f32 v[160:161], v[162:163], v[160:161]
	v_and_b32_e32 v159, 0xffff0000, v119
	v_and_b32_e32 v158, 0xffff0000, v118
	v_pk_add_f32 v[160:161], v[164:165], v[160:161]
	v_lshlrev_b32_e32 v157, 16, v119
	v_lshlrev_b32_e32 v156, 16, v118
	v_lshlrev_b32_e32 v118, 16, v116
	v_and_b32_e32 v119, 0xffff0000, v116
	v_lshlrev_b32_e32 v120, 16, v117
	v_lshlrev_b32_e32 v116, 16, v114
	v_pk_add_f32 v[160:161], v[160:161], v[160:161] op_sel_hi:[0,1]
	v_pk_mul_f32 v[162:163], v[158:159], v[158:159]
	v_and_b32_e32 v121, 0xffff0000, v117
	v_pk_fma_f32 v[162:163], v[156:157], v[156:157], v[162:163]
	v_mul_f32_e32 v117, v118, v118
	v_mul_f32_e32 v165, v119, v119
	v_mul_f32_e32 v160, v120, v120
	v_mov_b32_e32 v164, v116
	v_and_b32_e32 v180, 0xffff0000, v114
	v_lshlrev_b32_e32 v114, 16, v115
	v_and_b32_e32 v115, 0xffff0000, v115
	v_pk_add_f32 v[162:163], v[162:163], v[162:163] op_sel_hi:[0,1]
	v_pk_fma_f32 v[166:167], v[120:121], v[120:121], v[160:161] op_sel_hi:[1,1,0]
	v_pk_add_f32 v[164:165], v[116:117], v[164:165]
	v_mul_f32_e32 v166, v180, v180
	v_mul_f32_e32 v162, v114, v114
	v_mul_f32_e32 v160, v115, v115
	v_mul_f32_e32 v168, v116, v116
	v_mov_b32_e32 v169, v165
	v_pk_add_f32 v[164:165], v[168:169], v[166:167]
	v_pk_add_f32 v[160:161], v[162:163], v[160:161]
	v_lshlrev_b32_e32 v166, 16, v104
	v_pk_add_f32 v[160:161], v[164:165], v[160:161]
	v_and_b32_e32 v167, 0xffff0000, v104
	v_add_f32_e32 v117, v160, v161
	ds_bpermute_b32 v153, v1, v117
	v_lshlrev_b32_e32 v168, 16, v105
	v_and_b32_e32 v169, 0xffff0000, v105
	v_lshlrev_b32_e32 v170, 16, v102
	v_and_b32_e32 v171, 0xffff0000, v102
	s_waitcnt lgkmcnt(0)
	v_add_f32_e32 v117, v117, v153
	ds_bpermute_b32 v153, v132, v117
	v_lshlrev_b32_e32 v172, 16, v103
	v_and_b32_e32 v173, 0xffff0000, v103
	v_lshlrev_b32_e32 v174, 16, v100
	v_and_b32_e32 v175, 0xffff0000, v100
	s_waitcnt lgkmcnt(0)
	v_add_f32_e32 v117, v117, v153
	ds_bpermute_b32 v153, v133, v117
	v_lshlrev_b32_e32 v176, 16, v101
	v_and_b32_e32 v177, 0xffff0000, v101
	v_mov_b32_e32 v101, v147
	v_lshlrev_b32_e32 v138, 16, v130
	s_waitcnt lgkmcnt(0)
	v_add_f32_e32 v117, v117, v153
	ds_bpermute_b32 v153, v134, v117
	v_and_b32_e32 v139, 0xffff0000, v130
	v_lshlrev_b32_e32 v130, 16, v131
	v_and_b32_e32 v131, 0xffff0000, v131
	v_lshlrev_b32_e32 v140, 16, v112
	s_waitcnt lgkmcnt(0)
	v_add_f32_e32 v117, v117, v153
	ds_bpermute_b32 v153, v135, v117
	v_and_b32_e32 v141, 0xffff0000, v112
	v_lshlrev_b32_e32 v112, 16, v113
	v_and_b32_e32 v113, 0xffff0000, v113
	v_lshlrev_b32_e32 v160, 16, v110
	s_waitcnt lgkmcnt(0)
	v_add_f32_e32 v104, v117, v153
	ds_bpermute_b32 v105, v136, v104
	v_and_b32_e32 v161, 0xffff0000, v110
	v_lshlrev_b32_e32 v110, 16, v111
	v_and_b32_e32 v111, 0xffff0000, v111
	v_lshlrev_b32_e32 v162, 16, v108
	s_waitcnt lgkmcnt(0)
	v_add_f32_e32 v102, v104, v105
	v_fmamk_f32 v102, v102, 0x3a000000, v137
	v_mul_f32_e32 v103, 0x4b800000, v102
	v_cmp_gt_f32_e32 vcc, s12, v102
	v_and_b32_e32 v163, 0xffff0000, v108
	v_lshlrev_b32_e32 v108, 16, v109
	v_cndmask_b32_e32 v102, v102, v103, vcc
	v_rsq_f32_e32 v102, v102
	v_and_b32_e32 v109, 0xffff0000, v109
	v_mov_b32_e32 v153, v179
	v_lshlrev_b32_e32 v164, 16, v106
	v_mul_f32_e32 v100, 0x45800000, v102
	v_cndmask_b32_e32 v178, v102, v100, vcc
	v_mov_b32_e32 v100, v145
	v_pk_mul_f32 v[102:103], v[178:179], v[100:101] op_sel_hi:[0,1]
	v_mov_b32_e32 v100, v149
	v_mov_b32_e32 v101, v129
	v_pk_mul_f32 v[100:101], v[178:179], v[100:101] op_sel_hi:[0,1]
	v_mov_b32_e32 v145, v146
	v_mov_b32_e32 v149, v128
	v_pk_fma_f32 v[100:101], v[4:5], v[100:101], v[130:131]
	v_pk_mul_f32 v[130:131], v[178:179], v[144:145] op_sel_hi:[0,1]
	v_pk_mul_f32 v[104:105], v[178:179], v[148:149] op_sel_hi:[0,1]
	v_pk_fma_f32 v[102:103], v[2:3], v[102:103], v[138:139]
	v_pk_fma_f32 v[104:105], v[12:13], v[104:105], v[112:113]
	v_pk_fma_f32 v[112:113], v[10:11], v[130:131], v[140:141]
	v_mov_b32_e32 v140, v103
	v_mov_b32_e32 v141, v113
	v_mov_b32_e32 v138, v102
	v_mov_b32_e32 v139, v112
	v_pk_mul_f32 v[140:141], v[140:141], v[140:141]
	v_mov_b32_e32 v144, v101
	v_mov_b32_e32 v145, v105
	v_mov_b32_e32 v128, v126
	v_mov_b32_e32 v129, v124
	v_mov_b32_e32 v124, v127
	v_pk_fma_f32 v[138:139], v[138:139], v[138:139], v[140:141]
	v_mov_b32_e32 v140, v100
	v_mov_b32_e32 v141, v104
	v_pk_mul_f32 v[144:145], v[144:145], v[144:145]
	v_pk_mul_f32 v[128:129], v[178:179], v[128:129] op_sel_hi:[0,1]
	v_pk_mul_f32 v[124:125], v[178:179], v[124:125] op_sel_hi:[0,1]
	v_pk_fma_f32 v[140:141], v[140:141], v[140:141], v[144:145]
	v_pk_fma_f32 v[110:111], v[16:17], v[124:125], v[110:111]
	v_pk_fma_f32 v[124:125], v[14:15], v[128:129], v[160:161]
	v_pk_mul_f32 v[126:127], v[178:179], v[150:151] op_sel_hi:[0,1]
	v_pk_mul_f32 v[122:123], v[178:179], v[122:123] op_sel_hi:[0,1]
	v_pk_add_f32 v[138:139], v[138:139], v[140:141]
	v_pk_fma_f32 v[108:109], v[28:29], v[122:123], v[108:109]
	v_pk_fma_f32 v[122:123], v[26:27], v[126:127], v[162:163]
	v_pk_add_f32 v[138:139], v[138:139], v[138:139] op_sel_hi:[0,1]
	v_pk_mul_f32 v[140:141], v[110:111], v[110:111]
	v_pk_mul_f32 v[144:145], v[124:125], v[124:125]
	v_mul_f32_e32 v138, v122, v122
	v_pk_mov_b32 v[146:147], v[144:145], v[140:141] op_sel:[1,0]
	v_mov_b32_e32 v145, v141
	v_and_b32_e32 v165, 0xffff0000, v106
	v_lshlrev_b32_e32 v106, 16, v107
	v_and_b32_e32 v107, 0xffff0000, v107
	v_pk_mul_f32 v[126:127], v[178:179], v[152:153] op_sel_hi:[0,1]
	v_pk_mul_f32 v[128:129], v[178:179], v[154:155] op_sel_hi:[0,1]
	v_pk_add_f32 v[140:141], v[146:147], v[144:145]
	v_pk_fma_f32 v[144:145], v[122:123], v[122:123], v[138:139] op_sel_hi:[1,1,0]
	v_mul_f32_e32 v138, v108, v108
	v_pk_fma_f32 v[106:107], v[36:37], v[128:129], v[106:107]
	v_pk_fma_f32 v[126:127], v[34:35], v[126:127], v[164:165]
	v_pk_add_f32 v[140:141], v[140:141], v[140:141] op_sel_hi:[0,1]
	v_pk_fma_f32 v[146:147], v[108:109], v[108:109], v[138:139] op_sel_hi:[1,1,0]
	v_mov_b32_e32 v128, v156
	v_mov_b32_e32 v129, v158
	v_mov_b32_e32 v158, v157
	v_mul_f32_e32 v144, v126, v126
	v_mul_f32_e32 v146, v127, v127
	v_mul_f32_e32 v140, v106, v106
	v_mul_f32_e32 v138, v107, v107
	v_pk_mul_f32 v[128:129], v[178:179], v[128:129] op_sel_hi:[0,1]
	v_pk_mul_f32 v[130:131], v[178:179], v[158:159] op_sel_hi:[0,1]
	v_pk_add_f32 v[144:145], v[144:145], v[146:147]
	v_pk_add_f32 v[138:139], v[140:141], v[138:139]
	v_pk_fma_f32 v[130:131], v[40:41], v[130:131], v[168:169]
	v_pk_fma_f32 v[128:129], v[38:39], v[128:129], v[166:167]
	v_pk_mul_f32 v[118:119], v[178:179], v[118:119] op_sel_hi:[0,1]
	v_pk_add_f32 v[138:139], v[144:145], v[138:139]
	v_pk_mul_f32 v[120:121], v[178:179], v[120:121] op_sel_hi:[0,1]
	v_pk_fma_f32 v[118:119], v[50:51], v[118:119], v[170:171]
	v_pk_add_f32 v[138:139], v[138:139], v[138:139] op_sel_hi:[0,1]
	v_pk_mul_f32 v[140:141], v[130:131], v[130:131]
	v_pk_mul_f32 v[144:145], v[128:129], v[128:129]
	v_pk_fma_f32 v[120:121], v[52:53], v[120:121], v[172:173]
	v_mov_b32_e32 v117, v180
	v_pk_mov_b32 v[146:147], v[144:145], v[140:141] op_sel:[1,0]
	v_mov_b32_e32 v145, v141
	v_mul_f32_e32 v138, v118, v118
	v_pk_mul_f32 v[116:117], v[178:179], v[116:117] op_sel_hi:[0,1]
	v_pk_mul_f32 v[114:115], v[178:179], v[114:115] op_sel_hi:[0,1]
	v_pk_add_f32 v[140:141], v[146:147], v[144:145]
	v_pk_fma_f32 v[144:145], v[118:119], v[118:119], v[138:139] op_sel_hi:[1,1,0]
	v_mul_f32_e32 v138, v120, v120
	v_pk_fma_f32 v[114:115], v[56:57], v[114:115], v[176:177]
	v_pk_fma_f32 v[116:117], v[54:55], v[116:117], v[174:175]
	v_pk_add_f32 v[140:141], v[140:141], v[140:141] op_sel_hi:[0,1]
	v_pk_fma_f32 v[146:147], v[120:121], v[120:121], v[138:139] op_sel_hi:[1,1,0]
	v_mul_f32_e32 v144, v116, v116
	v_mul_f32_e32 v146, v117, v117
	v_mul_f32_e32 v140, v114, v114
	v_mul_f32_e32 v138, v115, v115
	v_pk_add_f32 v[144:145], v[144:145], v[146:147]
	v_pk_add_f32 v[138:139], v[140:141], v[138:139]
	v_cvt_pk_bf16_f32 v140, v102, v103
	v_pk_add_f32 v[138:139], v[144:145], v[138:139]
	v_cvt_pk_bf16_f32 v141, v100, v101
	v_add_f32_e32 v144, v138, v139
	ds_bpermute_b32 v145, v1, v144
	v_lshl_add_u64 v[138:139], s[4:5], 0, v[66:67]
	s_add_u32 s4, s4, s6
	s_addc_u32 s5, s5, s7
	s_add_u32 s8, s8, s6
	s_waitcnt lgkmcnt(0)
	v_add_f32_e32 v146, v144, v145
	ds_bpermute_b32 v147, v132, v146
	v_add_co_u32_e32 v144, vcc, s3, v138
	s_addc_u32 s9, s9, s7
	s_nop 0
	v_addc_co_u32_e32 v145, vcc, 0, v139, vcc
	s_waitcnt lgkmcnt(0)
	v_add_f32_e32 v146, v146, v147
	ds_bpermute_b32 v147, v133, v146
	global_store_dwordx2 v[144:145], v[140:141], off nt
	v_cvt_pk_bf16_f32 v140, v112, v113
	v_cvt_pk_bf16_f32 v141, v104, v105
	global_store_dwordx2 v[144:145], v[140:141], off offset:512 nt
	s_waitcnt lgkmcnt(0)
	v_add_f32_e32 v146, v146, v147
	ds_bpermute_b32 v147, v134, v146
	v_cvt_pk_bf16_f32 v140, v124, v125
	v_cvt_pk_bf16_f32 v141, v110, v111
	global_store_dwordx2 v[144:145], v[140:141], off offset:1024 nt
	v_cvt_pk_bf16_f32 v140, v122, v123
	s_waitcnt lgkmcnt(0)
	v_add_f32_e32 v146, v146, v147
	ds_bpermute_b32 v147, v135, v146
	v_cvt_pk_bf16_f32 v141, v108, v109
	global_store_dwordx2 v[144:145], v[140:141], off offset:1536 nt
	v_cvt_pk_bf16_f32 v140, v126, v127
	v_cvt_pk_bf16_f32 v141, v106, v107
	s_waitcnt lgkmcnt(0)
	v_add_f32_e32 v146, v146, v147
	ds_bpermute_b32 v147, v136, v146
	global_store_dwordx2 v[144:145], v[140:141], off offset:2048 nt
	v_cvt_pk_bf16_f32 v140, v128, v129
	v_cvt_pk_bf16_f32 v141, v130, v131
	global_store_dwordx2 v[144:145], v[140:141], off offset:2560 nt
	v_cvt_pk_bf16_f32 v140, v118, v119
	v_cvt_pk_bf16_f32 v141, v120, v121
	global_store_dwordx2 v[144:145], v[140:141], off offset:3072 nt
	s_waitcnt lgkmcnt(0)
	v_add_f32_e32 v140, v146, v147
	v_fmamk_f32 v140, v140, 0x3a000000, v137
	v_mul_f32_e32 v141, 0x4b800000, v140
	v_cmp_gt_f32_e32 vcc, s12, v140
	s_nop 1
	v_cndmask_b32_e32 v140, v140, v141, vcc
	v_rsq_f32_e32 v146, v140
	v_cvt_pk_bf16_f32 v140, v116, v117
	v_cvt_pk_bf16_f32 v141, v114, v115
	global_store_dwordx2 v[144:145], v[140:141], off offset:3584 nt
	v_mul_f32_e32 v140, 0x45800000, v146
	v_cndmask_b32_e32 v140, v146, v140, vcc
	v_pk_mul_f32 v[102:103], v[102:103], v[140:141] op_sel_hi:[1,0]
	v_pk_mul_f32 v[100:101], v[100:101], v[140:141] op_sel_hi:[1,0]
	v_pk_mul_f32 v[102:103], v[6:7], v[102:103]
	v_pk_mul_f32 v[100:101], v[8:9], v[100:101]
	v_cvt_pk_bf16_f32 v102, v102, v103
	v_cvt_pk_bf16_f32 v103, v100, v101
	v_add_co_u32_e32 v100, vcc, s13, v138
	v_pk_mul_f32 v[104:105], v[104:105], v[140:141] op_sel_hi:[1,0]
	s_nop 0
	v_addc_co_u32_e32 v101, vcc, 0, v139, vcc
	global_store_dwordx2 v[100:101], v[102:103], off
	v_pk_mul_f32 v[102:103], v[112:113], v[140:141] op_sel_hi:[1,0]
	v_pk_mul_f32 v[104:105], v[20:21], v[104:105]
	v_pk_mul_f32 v[102:103], v[18:19], v[102:103]
	s_andn2_b64 vcc, exec, s[10:11]
	v_cvt_pk_bf16_f32 v102, v102, v103
	v_cvt_pk_bf16_f32 v103, v104, v105
	global_store_dwordx2 v[100:101], v[102:103], off offset:512
	v_pk_mul_f32 v[102:103], v[124:125], v[140:141] op_sel_hi:[1,0]
	v_pk_mul_f32 v[104:105], v[110:111], v[140:141] op_sel_hi:[1,0]
	v_pk_mul_f32 v[102:103], v[22:23], v[102:103]
	v_pk_mul_f32 v[104:105], v[24:25], v[104:105]
	v_cvt_pk_bf16_f32 v102, v102, v103
	v_cvt_pk_bf16_f32 v103, v104, v105
	global_store_dwordx2 v[100:101], v[102:103], off offset:1024
	v_pk_mul_f32 v[102:103], v[122:123], v[140:141] op_sel_hi:[1,0]
	v_pk_mul_f32 v[104:105], v[108:109], v[140:141] op_sel_hi:[1,0]
	v_pk_mul_f32 v[102:103], v[30:31], v[102:103]
	v_pk_mul_f32 v[104:105], v[32:33], v[104:105]
	v_cvt_pk_bf16_f32 v102, v102, v103
	v_cvt_pk_bf16_f32 v103, v104, v105
	global_store_dwordx2 v[100:101], v[102:103], off offset:1536
	v_pk_mul_f32 v[102:103], v[126:127], v[140:141] op_sel_hi:[1,0]
	v_pk_mul_f32 v[104:105], v[106:107], v[140:141] op_sel_hi:[1,0]
	v_pk_mul_f32 v[102:103], v[42:43], v[102:103]
	v_pk_mul_f32 v[104:105], v[44:45], v[104:105]
	v_cvt_pk_bf16_f32 v102, v102, v103
	v_cvt_pk_bf16_f32 v103, v104, v105
	global_store_dwordx2 v[100:101], v[102:103], off offset:2048
	v_pk_mul_f32 v[102:103], v[128:129], v[140:141] op_sel_hi:[1,0]
	v_pk_mul_f32 v[104:105], v[130:131], v[140:141] op_sel_hi:[1,0]
	v_pk_mul_f32 v[102:103], v[46:47], v[102:103]
	v_pk_mul_f32 v[104:105], v[48:49], v[104:105]
	v_cvt_pk_bf16_f32 v102, v102, v103
	v_cvt_pk_bf16_f32 v103, v104, v105
	global_store_dwordx2 v[100:101], v[102:103], off offset:2560
	v_pk_mul_f32 v[102:103], v[118:119], v[140:141] op_sel_hi:[1,0]
	v_pk_mul_f32 v[104:105], v[120:121], v[140:141] op_sel_hi:[1,0]
	s_waitcnt vmcnt(15)
	v_pk_mul_f32 v[102:103], v[58:59], v[102:103]
	v_pk_mul_f32 v[104:105], v[60:61], v[104:105]
	v_cvt_pk_bf16_f32 v102, v102, v103
	v_cvt_pk_bf16_f32 v103, v104, v105
	global_store_dwordx2 v[100:101], v[102:103], off offset:3072
	v_pk_mul_f32 v[102:103], v[116:117], v[140:141] op_sel_hi:[1,0]
	v_pk_mul_f32 v[104:105], v[114:115], v[140:141] op_sel_hi:[1,0]
	s_waitcnt vmcnt(15)
	v_pk_mul_f32 v[102:103], v[62:63], v[102:103]
	v_pk_mul_f32 v[104:105], v[64:65], v[104:105]
	v_cvt_pk_bf16_f32 v102, v102, v103
	v_cvt_pk_bf16_f32 v103, v104, v105
	global_store_dwordx2 v[100:101], v[102:103], off offset:3584
	v_mov_b64_e32 v[114:115], v[82:83]
	v_mov_b64_e32 v[116:117], v[84:85]
	v_mov_b64_e32 v[118:119], v[86:87]
	v_mov_b64_e32 v[120:121], v[88:89]
	v_mov_b64_e32 v[122:123], v[90:91]
	v_mov_b64_e32 v[124:125], v[92:93]
	v_mov_b64_e32 v[126:127], v[94:95]
	v_mov_b64_e32 v[128:129], v[96:97]
	v_mov_b64_e32 v[130:131], v[68:69]
	v_mov_b64_e32 v[112:113], v[70:71]
	v_mov_b64_e32 v[110:111], v[72:73]
	v_mov_b64_e32 v[108:109], v[74:75]
	v_mov_b64_e32 v[106:107], v[76:77]
	v_mov_b64_e32 v[104:105], v[78:79]
	v_mov_b64_e32 v[102:103], v[80:81]
	v_mov_b64_e32 v[100:101], v[98:99]
	s_cbranch_vccz .LBB0_1352
